# static s_setprio 1 for the GLA prep-role waves (0-3) during the scan, on top of the nt-policy version
# speedup vs baseline: 1.0244x; 1.0086x over previous
; __device__ __forceinline__ unsigned cvt_pk_bf16(float lo, float hi) { unsigned r; asm volatile("v_cvt_pk_bf16_f32 %0, %1, %2" : "=v"(r) : "v"(lo), "v"(hi)); return r; }
; __device__ __forceinline__ void gla_prep(const Params& p, unsigned char* lds, int l, int item, int tid) {
;     ...
;     { const float* w2 = (dir ? p.w_a2_bwd : p.w_a2_fwd) + (size_t)l * 16 * 256 + c.h * 64 + c.ch; u32x4 w = (u32x4){0u, 0u, 0u, 0u};
;       if (c.q4 < 2) { float t[8];
; #pragma unroll
;           for (int i = 0; i < 8; ++i) t[i] = w2[(8 * c.q4 + i) * 256];
;           w.x = cvt_pk_bf16(t[0], t[1]); w.y = cvt_pk_bf16(t[2], t[3]); w.z = cvt_pk_bf16(t[4], t[5]); w.w = cvt_pk_bf16(t[6], t[7]); }
;       c.w2f = __builtin_bit_cast(bf16x8, w); c.bias = (dir ? p.b_a_bwd : p.b_a_fwd)[l * 256 + c.h * 64 + c.ch]; }
; PHASE_FN void gla_item(const Params& p, unsigned char* lds, int l, int item) {
;     ...
;     if (tid < 256) gla_prep(p, lds, l, item, tid); else gla_mma(p, lds, l, item, tid);
.LBB0_282:
	s_andn2_saveexec_b64 s[24:25], s[24:25]
	s_cbranch_execz .LBB0_352
	s_setprio 1
	v_readfirstlane_b32 s5, v106
	s_ashr_i32 s4, s5, 6
	s_waitcnt vmcnt(0)
	v_mov_b32_e32 v0, 0
	v_lshl_or_b32 v64, s4, 4, v108
	v_cmp_gt_u32_e64 s[40:41], 2, v107
	v_mov_b32_e32 v1, v0
	v_mov_b32_e32 v2, v0
	v_mov_b32_e32 v3, v0
	s_and_saveexec_b64 s[26:27], s[40:41]
	v_readlane_b32 s14, v246, 56
	v_readlane_b32 s15, v246, 57
	s_cbranch_execz .LBB0_285
	s_lshl_b32 s6, s14, 14
	v_readlane_b32 s7, v247, 46
	s_add_u32 s6, s7, s6
	v_readlane_b32 s7, v247, 47
	v_ashrrev_i32_e32 v65, 31, v64
	s_addc_u32 s7, s7, 0
	v_lshl_add_u64 v[0:1], v[64:65], 2, s[6:7]
	v_lshlrev_b32_e32 v152, 13, v107
	v_lshl_add_u64 v[0:1], v[0:1], 0, v[152:153]
	s_movk_i32 s6, 0x1000
	v_add_co_u32_e32 v2, vcc, s6, v0
	s_nop 1
	v_addc_co_u32_e32 v3, vcc, 0, v1, vcc
	global_load_dword v4, v[0:1], off offset:1024
	global_load_dword v5, v[0:1], off offset:2048
	global_load_dword v6, v[2:3], off offset:3072
	global_load_dword v7, v[2:3], off offset:1024
	global_load_dword v8, v[0:1], off offset:3072
	s_nop 0
	global_load_dword v0, v[0:1], off
	s_nop 0
	global_load_dword v9, v[2:3], off
	s_nop 0
	global_load_dword v3, v[2:3], off offset:2048
	s_waitcnt vmcnt(2)
	v_cvt_pk_bf16_f32 v0, v0, v4
	v_cvt_pk_bf16_f32 v1, v5, v8
	s_waitcnt vmcnt(1)
	v_cvt_pk_bf16_f32 v2, v9, v7
	s_waitcnt vmcnt(0)
	v_cvt_pk_bf16_f32 v3, v3, v6

; PHASE_FN void gla_item(const Params& p, unsigned char* lds, int l, int item) {
;     int tid = threadIdx.x; asm volatile("" : "+v"(tid));
;     if (tid < 256) gla_prep(p, lds, l, item, tid); else gla_mma(p, lds, l, item, tid);
;     __syncthreads();
.LBB0_351:
	s_setprio 0
	s_waitcnt lgkmcnt(0)
	s_barrier
	s_waitcnt lgkmcnt(0)
	s_barrier
	v_readlane_b32 s50, v246, 43
	v_readlane_b32 s51, v246, 44
